# combination: rstd loads hoisted to tile top, W_uv and indexer-key operand-order layouts, top-k popcount split 4+4
# speedup vs baseline: 1.0024x; 1.0002x over previous
; __device__ __forceinline__ void prep_unit(const Args& a, LAS unsigned char* lds, int b, int kt, int tid) {
;     const GAS bf16* z = (const GAS bf16*)(a.ws + WS_Z);
;     LAS bf16* tT = (LAS bf16*)lds;
;     const int key = tid >> 3, ch = tid & 7; const size_t row = (size_t)b * SEQ + kt * 64 + key;
;     const u32x4 d0 = *(const GAS u32x4*)(z + row * ZW + ZDC + 16 * ch), d1 = *(const GAS u32x4*)(z + row * ZW + ZDC + 16 * ch + 8);
;     const u32x4 k0 = *(const GAS u32x4*)(z + row * ZW + ZIK + 8 * ch);
;     float v[16]; float ss = 0.f;
; #pragma unroll
;     for (int i = 0; i < 4; ++i) { v[2 * i] = bflo(d0[i]); v[2 * i + 1] = bfhi(d0[i]); v[8 + 2 * i] = bflo(d1[i]); v[8 + 2 * i + 1] = bfhi(d1[i]); }
; #pragma unroll
;     for (int i = 0; i < 16; ++i) ss += v[i] * v[i];
;     ss += __shfl_xor(ss, 1); ss += __shfl_xor(ss, 2); ss += __shfl_xor(ss, 4);
;     const float r = rsqrtf(ss * (1.f / 128.f) + EPS);
;     unsigned short o[16];
;     u32x4 w0, w1;
; #pragma unroll
;     for (int i = 0; i < 4; ++i) { w0[i] = pk2(v[2 * i] * r, v[2 * i + 1] * r); w1[i] = pk2(v[8 + 2 * i] * r, v[8 + 2 * i + 1] * r);
;         o[2 * i] = (unsigned short)(w0[i] & 0xffffu); o[2 * i + 1] = (unsigned short)(w0[i] >> 16); o[8 + 2 * i] = (unsigned short)(w1[i] & 0xffffu); o[8 + 2 * i + 1] = (unsigned short)(w1[i] >> 16); }
;     GAS bf16* ckv = (GAS bf16*)(a.ws + WS_CKV);
;     *(GAS u32x4*)(ckv + row * 128 + 16 * ch) = w0; *(GAS u32x4*)(ckv + row * 128 + 16 * ch + 8) = w1;
; #pragma unroll
;     for (int i = 0; i < 16; ++i) tT[(16 * ch + i) * 72 + key] = o[i];
;     float kv[8]; float s2 = 0.f;
; #pragma unroll
;     for (int i = 0; i < 4; ++i) { kv[2 * i] = bflo(k0[i]); kv[2 * i + 1] = bfhi(k0[i]); }
; #pragma unroll
;     for (int i = 0; i < 8; ++i) s2 += kv[i] * kv[i];
;     s2 += __shfl_xor(s2, 1); s2 += __shfl_xor(s2, 2); s2 += __shfl_xor(s2, 4);
;     const float r2 = rsqrtf(s2 * (1.f / 64.f) + EPS);
;     u32x4 wk;
; #pragma unroll
;     for (int i = 0; i < 4; ++i) wk[i] = pk2(kv[2 * i] * r2, kv[2 * i + 1] * r2);
;     *(GAS u32x4*)((GAS bf16*)(a.ws + WS_IKN) + row * 64 + 8 * ch) = wk;
;     __syncthreads();
;     const int c = tid >> 2, q4 = tid & 3;
;     const u32x4 t0 = *(const LAS u32x4*)(tT + c * 72 + 16 * q4), t1 = *(const LAS u32x4*)(tT + c * 72 + 16 * q4 + 8);
;     GAS bf16* dst = (GAS bf16*)(a.ws + WS_CKVT) + ((size_t)b * 128 + c) * SEQ + kt * 64 + 16 * q4;
.Lwuv_done:
	v_readlane_b32 s0, v254, 7
	v_readlane_b32 s1, v254, 8
	s_and_b64 vcc, exec, s[0:1]
	s_waitcnt lgkmcnt(0)
	s_barrier
	s_cbranch_vccnz .LBB0_930
	v_mbcnt_hi_u32_b32 v2, -1, v225
	v_and_b32_e32 v4, 64, v2
	v_xor_b32_e32 v3, 1, v2
	v_add_u32_e32 v4, 64, v4
	v_cmp_lt_i32_e32 vcc, v3, v4
	v_mov_b32_e32 v1, 0
	v_lshlrev_b32_e32 v8, 4, v252
	v_cndmask_b32_e32 v3, v2, v3, vcc
	v_lshlrev_b32_e32 v18, 2, v3
	v_xor_b32_e32 v3, 2, v2
	v_cmp_lt_i32_e32 vcc, v3, v4
	v_lshrrev_b32_e32 v6, 2, v252
	v_and_b32_e32 v16, 48, v8
	v_cndmask_b32_e32 v3, v2, v3, vcc
	v_lshlrev_b32_e32 v19, 2, v3
	v_xor_b32_e32 v3, 4, v2
	v_cmp_lt_i32_e32 vcc, v3, v4
	v_lshlrev_b32_e32 v0, 4, v226
	s_mov_b64 s[4:5], 0x1b400000
	v_cndmask_b32_e32 v2, v2, v3, vcc
	v_lshlrev_b32_e32 v20, 2, v2
	v_lshlrev_b32_e32 v2, 5, v226
	v_mov_b32_e32 v3, v1
	v_lshl_add_u64 v[2:3], s[80:81], 0, v[2:3]
	v_mul_u32_u24_e32 v7, 0x90, v6
	v_lshlrev_b32_e32 v8, 1, v16
	v_lshl_add_u64 v[2:3], v[2:3], 0, s[4:5]
	v_lshlrev_b32_e32 v4, 8, v226
	v_mov_b32_e32 v5, v1
	v_lshl_add_u64 v[4:5], s[80:81], 0, v[4:5]
	s_mov_b64 s[4:5], 0x1c400000
	v_add3_u32 v21, 0, v7, v8
	v_lshlrev_b32_e32 v6, 12, v6
	v_mov_b32_e32 v7, v1
	s_add_u32 s2, s80, 0x8400000
	v_lshrrev_b32_e32 v15, 3, v252
	v_lshl_add_u64 v[4:5], v[4:5], 0, s[4:5]
	v_lshl_add_u64 v[6:7], s[80:81], 0, v[6:7]
	s_mov_b64 s[4:5], 0x1bc00000
	s_addc_u32 s3, s81, 0
	v_lshlrev_b32_e32 v12, 3, v226
	v_lshl_add_u32 v17, v15, 1, 0
	v_mul_u32_u24_e32 v22, 0x900, v226
	v_lshl_add_u64 v[6:7], v[6:7], 0, s[4:5]
	s_mov_b32 s4, 0x3c800000
	s_mov_b32 s1, 0
	s_lshl_b32 s8, s89, 6
	s_lshl_b32 s9, s84, 6
	s_movk_i32 s10, 0x1e00
	v_mov_b64_e32 v[8:9], s[2:3]
	v_lshlrev_b32_e32 v10, 1, v0
	v_mov_b32_e32 v11, v1
	s_mov_b64 s[2:3], 0x1800
	s_movk_i32 s11, 0x1000
	v_lshlrev_b32_e32 v12, 1, v12
	v_mov_b32_e32 v13, v1
	s_brev_b32 s5, 60
	v_mov_b32_e32 v14, 0x358637bd
	s_mov_b32 s12, 0x800000
	v_add_u32_e32 v22, v17, v22
	v_lshlrev_b32_e32 v16, 1, v16
	v_mov_b32_e32 v17, v1
	s_mov_b32 s13, s89
